# instruction selection at GEMM unit top: redundant second accumulator zero-init removed where the first dominates it, remaining zero-inits written as 64 v_mov_b64 instead of 128 v_mov_b32 (on top of v1
# speedup vs baseline: 1.0106x; 1.0106x over previous
.LBB0_133:
	s_ashr_i32 s19, s18, 31
	s_lshl_b64 s[20:21], s[18:19], 20
	s_add_u32 s20, s30, s20
	s_addc_u32 s21, s31, s21
	s_ashr_i32 s17, s16, 31
	s_lshl_b64 s[22:23], s[16:17], 20
	v_readlane_b32 s28, v255, 37
	v_readlane_b32 s29, v255, 38
	s_add_u32 s22, s28, s22
	s_addc_u32 s23, s29, s23
	s_andn2_b64 vcc, exec, s[10:11]
	v_mov_b64_e32 v[2:3], 0
	v_mov_b64_e32 v[4:5], 0
	v_mov_b64_e32 v[6:7], 0
	v_mov_b64_e32 v[8:9], 0
	v_mov_b64_e32 v[10:11], 0
	v_mov_b64_e32 v[12:13], 0
	v_mov_b64_e32 v[14:15], 0
	v_mov_b64_e32 v[16:17], 0
	v_mov_b64_e32 v[18:19], 0
	v_mov_b64_e32 v[20:21], 0
	v_mov_b64_e32 v[22:23], 0
	v_mov_b64_e32 v[24:25], 0
	v_mov_b64_e32 v[26:27], 0
	v_mov_b64_e32 v[28:29], 0
	v_mov_b64_e32 v[30:31], 0
	v_mov_b64_e32 v[32:33], 0
	v_mov_b64_e32 v[34:35], 0
	v_mov_b64_e32 v[36:37], 0
	v_mov_b64_e32 v[38:39], 0
	v_mov_b64_e32 v[40:41], 0
	v_mov_b64_e32 v[42:43], 0
	v_mov_b64_e32 v[44:45], 0
	v_mov_b64_e32 v[46:47], 0
	v_mov_b64_e32 v[48:49], 0
	v_mov_b64_e32 v[50:51], 0
	v_mov_b64_e32 v[52:53], 0
	v_mov_b64_e32 v[54:55], 0
	v_mov_b64_e32 v[56:57], 0
	v_mov_b64_e32 v[58:59], 0
	v_mov_b64_e32 v[60:61], 0
	v_mov_b64_e32 v[62:63], 0
	v_mov_b64_e32 v[64:65], 0
	v_mov_b64_e32 v[66:67], 0
	v_mov_b64_e32 v[68:69], 0
	v_mov_b64_e32 v[70:71], 0
	v_mov_b64_e32 v[72:73], 0
	v_mov_b64_e32 v[74:75], 0
	v_mov_b64_e32 v[76:77], 0
	v_mov_b64_e32 v[78:79], 0
	v_mov_b64_e32 v[80:81], 0
	v_mov_b64_e32 v[82:83], 0
	v_mov_b64_e32 v[84:85], 0
	v_mov_b64_e32 v[86:87], 0
	v_mov_b64_e32 v[88:89], 0
	v_mov_b64_e32 v[90:91], 0
	v_mov_b64_e32 v[92:93], 0
	v_mov_b64_e32 v[94:95], 0
	v_mov_b64_e32 v[96:97], 0
	v_mov_b64_e32 v[98:99], 0
	v_mov_b64_e32 v[100:101], 0
	v_mov_b64_e32 v[102:103], 0
	v_mov_b64_e32 v[104:105], 0
	v_mov_b64_e32 v[106:107], 0
	v_mov_b64_e32 v[108:109], 0
	v_mov_b64_e32 v[110:111], 0
	v_mov_b64_e32 v[112:113], 0
	v_mov_b64_e32 v[114:115], 0
	v_mov_b64_e32 v[116:117], 0
	v_mov_b64_e32 v[118:119], 0
	v_mov_b64_e32 v[120:121], 0
	v_mov_b64_e32 v[122:123], 0
	v_mov_b64_e32 v[124:125], 0
	v_mov_b64_e32 v[126:127], 0
	v_mov_b64_e32 v[128:129], 0
	s_cbranch_vccnz .LBB0_137
	s_and_b64 s[28:29], s[4:5], exec
	s_cselect_b32 s17, s21, s25
	s_cselect_b32 s19, s20, s24
	s_cselect_b32 s49, s23, s27
	s_cselect_b32 s50, s22, s26
	s_add_u32 s24, s24, 0x80080
	s_addc_u32 s25, s25, 0
	s_add_u32 s56, s26, 0x100
	s_addc_u32 s57, s27, 0
	s_mov_b32 s26, 0
	v_mov_b64_e32 v[2:3], 0
	v_mov_b64_e32 v[4:5], 0
	v_mov_b64_e32 v[6:7], 0
	v_mov_b64_e32 v[8:9], 0
	v_mov_b64_e32 v[10:11], 0
	v_mov_b64_e32 v[12:13], 0
	v_mov_b64_e32 v[14:15], 0
	v_mov_b64_e32 v[16:17], 0
	v_mov_b64_e32 v[18:19], 0
	v_mov_b64_e32 v[20:21], 0
	v_mov_b64_e32 v[22:23], 0
	v_mov_b64_e32 v[24:25], 0
	v_mov_b64_e32 v[26:27], 0
	v_mov_b64_e32 v[28:29], 0
	v_mov_b64_e32 v[30:31], 0
	v_mov_b64_e32 v[32:33], 0
	v_mov_b64_e32 v[34:35], 0
	v_mov_b64_e32 v[36:37], 0
	v_mov_b64_e32 v[38:39], 0
	v_mov_b64_e32 v[40:41], 0
	v_mov_b64_e32 v[42:43], 0
	v_mov_b64_e32 v[44:45], 0
	v_mov_b64_e32 v[46:47], 0
	v_mov_b64_e32 v[48:49], 0
	v_mov_b64_e32 v[50:51], 0
	v_mov_b64_e32 v[52:53], 0
	v_mov_b64_e32 v[54:55], 0
	v_mov_b64_e32 v[56:57], 0
	v_mov_b64_e32 v[58:59], 0
	v_mov_b64_e32 v[60:61], 0
	v_mov_b64_e32 v[62:63], 0
	v_mov_b64_e32 v[64:65], 0
	v_mov_b64_e32 v[66:67], 0
	v_mov_b64_e32 v[68:69], 0
	v_mov_b64_e32 v[70:71], 0
	v_mov_b64_e32 v[72:73], 0
	v_mov_b64_e32 v[74:75], 0
	v_mov_b64_e32 v[76:77], 0
	v_mov_b64_e32 v[78:79], 0
	v_mov_b64_e32 v[80:81], 0
	v_mov_b64_e32 v[82:83], 0
	v_mov_b64_e32 v[84:85], 0
	v_mov_b64_e32 v[86:87], 0
	v_mov_b64_e32 v[88:89], 0
	v_mov_b64_e32 v[90:91], 0
	v_mov_b64_e32 v[92:93], 0
	v_mov_b64_e32 v[94:95], 0
	v_mov_b64_e32 v[96:97], 0
	v_mov_b64_e32 v[98:99], 0
	v_mov_b64_e32 v[100:101], 0
	v_mov_b64_e32 v[102:103], 0
	v_mov_b64_e32 v[104:105], 0
	v_mov_b64_e32 v[106:107], 0
	v_mov_b64_e32 v[108:109], 0
	v_mov_b64_e32 v[110:111], 0
	v_mov_b64_e32 v[112:113], 0
	v_mov_b64_e32 v[114:115], 0
	v_mov_b64_e32 v[116:117], 0
	v_mov_b64_e32 v[118:119], 0
	v_mov_b64_e32 v[120:121], 0
	v_mov_b64_e32 v[122:123], 0
	v_mov_b64_e32 v[124:125], 0
	v_mov_b64_e32 v[126:127], 0
	v_mov_b64_e32 v[128:129], 0

.LBB0_265:
	s_ashr_i32 s25, s24, 31
	s_lshl_b64 s[26:27], s[24:25], 19
	s_add_u32 s26, s60, s26
	s_addc_u32 s27, s61, s27
	s_ashr_i32 s23, s22, 31
	s_lshl_b64 s[28:29], s[22:23], 19
	s_add_u32 s28, s54, s28
	s_addc_u32 s29, s55, s29
	s_andn2_b64 vcc, exec, s[16:17]
	v_mov_b64_e32 v[2:3], 0
	v_mov_b64_e32 v[4:5], 0
	v_mov_b64_e32 v[6:7], 0
	v_mov_b64_e32 v[8:9], 0
	v_mov_b64_e32 v[10:11], 0
	v_mov_b64_e32 v[12:13], 0
	v_mov_b64_e32 v[14:15], 0
	v_mov_b64_e32 v[16:17], 0
	v_mov_b64_e32 v[18:19], 0
	v_mov_b64_e32 v[20:21], 0
	v_mov_b64_e32 v[22:23], 0
	v_mov_b64_e32 v[24:25], 0
	v_mov_b64_e32 v[26:27], 0
	v_mov_b64_e32 v[28:29], 0
	v_mov_b64_e32 v[30:31], 0
	v_mov_b64_e32 v[32:33], 0
	v_mov_b64_e32 v[34:35], 0
	v_mov_b64_e32 v[36:37], 0
	v_mov_b64_e32 v[38:39], 0
	v_mov_b64_e32 v[40:41], 0
	v_mov_b64_e32 v[42:43], 0
	v_mov_b64_e32 v[44:45], 0
	v_mov_b64_e32 v[46:47], 0
	v_mov_b64_e32 v[48:49], 0
	v_mov_b64_e32 v[50:51], 0
	v_mov_b64_e32 v[52:53], 0
	v_mov_b64_e32 v[54:55], 0
	v_mov_b64_e32 v[56:57], 0
	v_mov_b64_e32 v[58:59], 0
	v_mov_b64_e32 v[60:61], 0
	v_mov_b64_e32 v[62:63], 0
	v_mov_b64_e32 v[64:65], 0
	v_mov_b64_e32 v[66:67], 0
	v_mov_b64_e32 v[68:69], 0
	v_mov_b64_e32 v[70:71], 0
	v_mov_b64_e32 v[72:73], 0
	v_mov_b64_e32 v[74:75], 0
	v_mov_b64_e32 v[76:77], 0
	v_mov_b64_e32 v[78:79], 0
	v_mov_b64_e32 v[80:81], 0
	v_mov_b64_e32 v[82:83], 0
	v_mov_b64_e32 v[84:85], 0
	v_mov_b64_e32 v[86:87], 0
	v_mov_b64_e32 v[88:89], 0
	v_mov_b64_e32 v[90:91], 0
	v_mov_b64_e32 v[92:93], 0
	v_mov_b64_e32 v[94:95], 0
	v_mov_b64_e32 v[96:97], 0
	v_mov_b64_e32 v[98:99], 0
	v_mov_b64_e32 v[100:101], 0
	v_mov_b64_e32 v[102:103], 0
	v_mov_b64_e32 v[104:105], 0
	v_mov_b64_e32 v[106:107], 0
	v_mov_b64_e32 v[108:109], 0
	v_mov_b64_e32 v[110:111], 0
	v_mov_b64_e32 v[112:113], 0
	v_mov_b64_e32 v[114:115], 0
	v_mov_b64_e32 v[116:117], 0
	v_mov_b64_e32 v[118:119], 0
	v_mov_b64_e32 v[120:121], 0
	v_mov_b64_e32 v[122:123], 0
	v_mov_b64_e32 v[124:125], 0
	v_mov_b64_e32 v[126:127], 0
	v_mov_b64_e32 v[128:129], 0
	s_cbranch_vccnz .LBB0_268
	s_and_b64 s[36:37], s[4:5], exec
	s_cselect_b32 s3, s27, s31
	s_cselect_b32 s7, s26, s30
	s_cselect_b32 s9, s29, s35
	s_cselect_b32 s23, s28, s34
	s_add_u32 s30, s30, 0x40080
	s_addc_u32 s31, s31, 0
	s_add_u32 s25, s34, 0x100
	s_addc_u32 s48, s35, 0
	s_mov_b32 s34, 0
	v_mov_b64_e32 v[2:3], 0
	v_mov_b64_e32 v[4:5], 0
	v_mov_b64_e32 v[6:7], 0
	v_mov_b64_e32 v[8:9], 0
	v_mov_b64_e32 v[10:11], 0
	v_mov_b64_e32 v[12:13], 0
	v_mov_b64_e32 v[14:15], 0
	v_mov_b64_e32 v[16:17], 0
	v_mov_b64_e32 v[18:19], 0
	v_mov_b64_e32 v[20:21], 0
	v_mov_b64_e32 v[22:23], 0
	v_mov_b64_e32 v[24:25], 0
	v_mov_b64_e32 v[26:27], 0
	v_mov_b64_e32 v[28:29], 0
	v_mov_b64_e32 v[30:31], 0
	v_mov_b64_e32 v[32:33], 0
	v_mov_b64_e32 v[34:35], 0
	v_mov_b64_e32 v[36:37], 0
	v_mov_b64_e32 v[38:39], 0
	v_mov_b64_e32 v[40:41], 0
	v_mov_b64_e32 v[42:43], 0
	v_mov_b64_e32 v[44:45], 0
	v_mov_b64_e32 v[46:47], 0
	v_mov_b64_e32 v[48:49], 0
	v_mov_b64_e32 v[50:51], 0
	v_mov_b64_e32 v[52:53], 0
	v_mov_b64_e32 v[54:55], 0
	v_mov_b64_e32 v[56:57], 0
	v_mov_b64_e32 v[58:59], 0
	v_mov_b64_e32 v[60:61], 0
	v_mov_b64_e32 v[62:63], 0
	v_mov_b64_e32 v[64:65], 0
	v_mov_b64_e32 v[66:67], 0
	v_mov_b64_e32 v[68:69], 0
	v_mov_b64_e32 v[70:71], 0
	v_mov_b64_e32 v[72:73], 0
	v_mov_b64_e32 v[74:75], 0
	v_mov_b64_e32 v[76:77], 0
	v_mov_b64_e32 v[78:79], 0
	v_mov_b64_e32 v[80:81], 0
	v_mov_b64_e32 v[82:83], 0
	v_mov_b64_e32 v[84:85], 0
	v_mov_b64_e32 v[86:87], 0
	v_mov_b64_e32 v[88:89], 0
	v_mov_b64_e32 v[90:91], 0
	v_mov_b64_e32 v[92:93], 0
	v_mov_b64_e32 v[94:95], 0
	v_mov_b64_e32 v[96:97], 0
	v_mov_b64_e32 v[98:99], 0
	v_mov_b64_e32 v[100:101], 0
	v_mov_b64_e32 v[102:103], 0
	v_mov_b64_e32 v[104:105], 0
	v_mov_b64_e32 v[106:107], 0
	v_mov_b64_e32 v[108:109], 0
	v_mov_b64_e32 v[110:111], 0
	v_mov_b64_e32 v[112:113], 0
	v_mov_b64_e32 v[114:115], 0
	v_mov_b64_e32 v[116:117], 0
	v_mov_b64_e32 v[118:119], 0
	v_mov_b64_e32 v[120:121], 0
	v_mov_b64_e32 v[122:123], 0
	v_mov_b64_e32 v[124:125], 0
	v_mov_b64_e32 v[126:127], 0
	v_mov_b64_e32 v[128:129], 0

.LBB0_345:
	s_ashr_i32 s25, s24, 31
	s_lshl_b64 s[26:27], s[24:25], 20
	s_add_u32 s26, s38, s26
	s_addc_u32 s27, s39, s27
	s_ashr_i32 s23, s22, 31
	s_lshl_b64 s[28:29], s[22:23], 20
	v_readlane_b32 s36, v255, 51
	v_readlane_b32 s37, v255, 52
	s_add_u32 s28, s36, s28
	s_addc_u32 s29, s37, s29
	s_andn2_b64 vcc, exec, s[16:17]
	v_mov_b64_e32 v[2:3], 0
	v_mov_b64_e32 v[4:5], 0
	v_mov_b64_e32 v[6:7], 0
	v_mov_b64_e32 v[8:9], 0
	v_mov_b64_e32 v[10:11], 0
	v_mov_b64_e32 v[12:13], 0
	v_mov_b64_e32 v[14:15], 0
	v_mov_b64_e32 v[16:17], 0
	v_mov_b64_e32 v[18:19], 0
	v_mov_b64_e32 v[20:21], 0
	v_mov_b64_e32 v[22:23], 0
	v_mov_b64_e32 v[24:25], 0
	v_mov_b64_e32 v[26:27], 0
	v_mov_b64_e32 v[28:29], 0
	v_mov_b64_e32 v[30:31], 0
	v_mov_b64_e32 v[32:33], 0
	v_mov_b64_e32 v[34:35], 0
	v_mov_b64_e32 v[36:37], 0
	v_mov_b64_e32 v[38:39], 0
	v_mov_b64_e32 v[40:41], 0
	v_mov_b64_e32 v[42:43], 0
	v_mov_b64_e32 v[44:45], 0
	v_mov_b64_e32 v[46:47], 0
	v_mov_b64_e32 v[48:49], 0
	v_mov_b64_e32 v[50:51], 0
	v_mov_b64_e32 v[52:53], 0
	v_mov_b64_e32 v[54:55], 0
	v_mov_b64_e32 v[56:57], 0
	v_mov_b64_e32 v[58:59], 0
	v_mov_b64_e32 v[60:61], 0
	v_mov_b64_e32 v[62:63], 0
	v_mov_b64_e32 v[64:65], 0
	v_mov_b64_e32 v[66:67], 0
	v_mov_b64_e32 v[68:69], 0
	v_mov_b64_e32 v[70:71], 0
	v_mov_b64_e32 v[72:73], 0
	v_mov_b64_e32 v[74:75], 0
	v_mov_b64_e32 v[76:77], 0
	v_mov_b64_e32 v[78:79], 0
	v_mov_b64_e32 v[80:81], 0
	v_mov_b64_e32 v[82:83], 0
	v_mov_b64_e32 v[84:85], 0
	v_mov_b64_e32 v[86:87], 0
	v_mov_b64_e32 v[88:89], 0
	v_mov_b64_e32 v[90:91], 0
	v_mov_b64_e32 v[92:93], 0
	v_mov_b64_e32 v[94:95], 0
	v_mov_b64_e32 v[96:97], 0
	v_mov_b64_e32 v[98:99], 0
	v_mov_b64_e32 v[100:101], 0
	v_mov_b64_e32 v[102:103], 0
	v_mov_b64_e32 v[104:105], 0
	v_mov_b64_e32 v[106:107], 0
	v_mov_b64_e32 v[108:109], 0
	v_mov_b64_e32 v[110:111], 0
	v_mov_b64_e32 v[112:113], 0
	v_mov_b64_e32 v[114:115], 0
	v_mov_b64_e32 v[116:117], 0
	v_mov_b64_e32 v[118:119], 0
	v_mov_b64_e32 v[120:121], 0
	v_mov_b64_e32 v[122:123], 0
	v_mov_b64_e32 v[124:125], 0
	v_mov_b64_e32 v[126:127], 0
	v_mov_b64_e32 v[128:129], 0
	s_cbranch_vccnz .LBB0_349
	s_and_b64 s[36:37], s[4:5], exec
	s_cselect_b32 s23, s27, s31
	s_cselect_b32 s25, s26, s30
	s_cselect_b32 s70, s29, s35
	s_cselect_b32 s71, s28, s34
	s_add_u32 s30, s30, 0x80080
	s_addc_u32 s31, s31, 0
	s_add_u32 s74, s34, 0x100
	s_addc_u32 s75, s35, 0
	s_mov_b32 s34, 0
	v_mov_b64_e32 v[2:3], 0
	v_mov_b64_e32 v[4:5], 0
	v_mov_b64_e32 v[6:7], 0
	v_mov_b64_e32 v[8:9], 0
	v_mov_b64_e32 v[10:11], 0
	v_mov_b64_e32 v[12:13], 0
	v_mov_b64_e32 v[14:15], 0
	v_mov_b64_e32 v[16:17], 0
	v_mov_b64_e32 v[18:19], 0
	v_mov_b64_e32 v[20:21], 0
	v_mov_b64_e32 v[22:23], 0
	v_mov_b64_e32 v[24:25], 0
	v_mov_b64_e32 v[26:27], 0
	v_mov_b64_e32 v[28:29], 0
	v_mov_b64_e32 v[30:31], 0
	v_mov_b64_e32 v[32:33], 0
	v_mov_b64_e32 v[34:35], 0
	v_mov_b64_e32 v[36:37], 0
	v_mov_b64_e32 v[38:39], 0
	v_mov_b64_e32 v[40:41], 0
	v_mov_b64_e32 v[42:43], 0
	v_mov_b64_e32 v[44:45], 0
	v_mov_b64_e32 v[46:47], 0
	v_mov_b64_e32 v[48:49], 0
	v_mov_b64_e32 v[50:51], 0
	v_mov_b64_e32 v[52:53], 0
	v_mov_b64_e32 v[54:55], 0
	v_mov_b64_e32 v[56:57], 0
	v_mov_b64_e32 v[58:59], 0
	v_mov_b64_e32 v[60:61], 0
	v_mov_b64_e32 v[62:63], 0
	v_mov_b64_e32 v[64:65], 0
	v_mov_b64_e32 v[66:67], 0
	v_mov_b64_e32 v[68:69], 0
	v_mov_b64_e32 v[70:71], 0
	v_mov_b64_e32 v[72:73], 0
	v_mov_b64_e32 v[74:75], 0
	v_mov_b64_e32 v[76:77], 0
	v_mov_b64_e32 v[78:79], 0
	v_mov_b64_e32 v[80:81], 0
	v_mov_b64_e32 v[82:83], 0
	v_mov_b64_e32 v[84:85], 0
	v_mov_b64_e32 v[86:87], 0
	v_mov_b64_e32 v[88:89], 0
	v_mov_b64_e32 v[90:91], 0
	v_mov_b64_e32 v[92:93], 0
	v_mov_b64_e32 v[94:95], 0
	v_mov_b64_e32 v[96:97], 0
	v_mov_b64_e32 v[98:99], 0
	v_mov_b64_e32 v[100:101], 0
	v_mov_b64_e32 v[102:103], 0
	v_mov_b64_e32 v[104:105], 0
	v_mov_b64_e32 v[106:107], 0
	v_mov_b64_e32 v[108:109], 0
	v_mov_b64_e32 v[110:111], 0
	v_mov_b64_e32 v[112:113], 0
	v_mov_b64_e32 v[114:115], 0
	v_mov_b64_e32 v[116:117], 0
	v_mov_b64_e32 v[118:119], 0
	v_mov_b64_e32 v[120:121], 0
	v_mov_b64_e32 v[122:123], 0
	v_mov_b64_e32 v[124:125], 0
	v_mov_b64_e32 v[126:127], 0
	v_mov_b64_e32 v[128:129], 0

.LBB0_372:
	s_andn2_b64 vcc, exec, s[20:21]
	v_mov_b64_e32 v[2:3], 0
	v_mov_b64_e32 v[4:5], 0
	v_mov_b64_e32 v[6:7], 0
	v_mov_b64_e32 v[8:9], 0
	v_mov_b64_e32 v[10:11], 0
	v_mov_b64_e32 v[12:13], 0
	v_mov_b64_e32 v[14:15], 0
	v_mov_b64_e32 v[16:17], 0
	v_mov_b64_e32 v[18:19], 0
	v_mov_b64_e32 v[20:21], 0
	v_mov_b64_e32 v[22:23], 0
	v_mov_b64_e32 v[24:25], 0
	v_mov_b64_e32 v[26:27], 0
	v_mov_b64_e32 v[28:29], 0
	v_mov_b64_e32 v[30:31], 0
	v_mov_b64_e32 v[32:33], 0
	v_mov_b64_e32 v[34:35], 0
	v_mov_b64_e32 v[36:37], 0
	v_mov_b64_e32 v[38:39], 0
	v_mov_b64_e32 v[40:41], 0
	v_mov_b64_e32 v[42:43], 0
	v_mov_b64_e32 v[44:45], 0
	v_mov_b64_e32 v[46:47], 0
	v_mov_b64_e32 v[48:49], 0
	v_mov_b64_e32 v[50:51], 0
	v_mov_b64_e32 v[52:53], 0
	v_mov_b64_e32 v[54:55], 0
	v_mov_b64_e32 v[56:57], 0
	v_mov_b64_e32 v[58:59], 0
	v_mov_b64_e32 v[60:61], 0
	v_mov_b64_e32 v[62:63], 0
	v_mov_b64_e32 v[64:65], 0
	v_mov_b64_e32 v[66:67], 0
	v_mov_b64_e32 v[68:69], 0
	v_mov_b64_e32 v[70:71], 0
	v_mov_b64_e32 v[72:73], 0
	v_mov_b64_e32 v[74:75], 0
	v_mov_b64_e32 v[76:77], 0
	v_mov_b64_e32 v[78:79], 0
	v_mov_b64_e32 v[80:81], 0
	v_mov_b64_e32 v[82:83], 0
	v_mov_b64_e32 v[84:85], 0
	v_mov_b64_e32 v[86:87], 0
	v_mov_b64_e32 v[88:89], 0
	v_mov_b64_e32 v[90:91], 0
	v_mov_b64_e32 v[92:93], 0
	v_mov_b64_e32 v[94:95], 0
	v_mov_b64_e32 v[96:97], 0
	v_mov_b64_e32 v[98:99], 0
	v_mov_b64_e32 v[100:101], 0
	v_mov_b64_e32 v[102:103], 0
	v_mov_b64_e32 v[104:105], 0
	v_mov_b64_e32 v[106:107], 0
	v_mov_b64_e32 v[108:109], 0
	v_mov_b64_e32 v[110:111], 0
	v_mov_b64_e32 v[112:113], 0
	v_mov_b64_e32 v[114:115], 0
	v_mov_b64_e32 v[116:117], 0
	v_mov_b64_e32 v[118:119], 0
	v_mov_b64_e32 v[120:121], 0
	v_mov_b64_e32 v[122:123], 0
	v_mov_b64_e32 v[124:125], 0
	v_mov_b64_e32 v[126:127], 0
	v_mov_b64_e32 v[128:129], 0
	s_cbranch_vccnz .LBB0_375
	s_add_u32 s77, s28, 0x100
	v_mov_b32_e32 v2, 0
	s_addc_u32 s78, s29, 0
	s_mov_b32 s30, 0

.LBB0_428:
	s_ashr_i32 s27, s26, 31
	s_ashr_i32 s25, s24, 31
	s_lshl_b64 s[8:9], s[26:27], 20
	s_lshl_b64 s[28:29], s[24:25], 8
	s_add_u32 s8, s3, s8
	s_addc_u32 s9, s42, s9
	s_add_u32 s28, s8, s28
	s_addc_u32 s29, s9, s29
	s_lshl_b64 s[8:9], s[24:25], 16
	v_readlane_b32 s25, v255, 47
	s_add_u32 s30, s25, s8
	v_readlane_b32 s8, v255, 48
	s_addc_u32 s31, s8, s9
	v_mov_b32_e32 v129, 0
	s_andn2_b64 vcc, exec, s[18:19]
	v_mov_b32_e32 v128, 0
	v_mov_b32_e32 v127, 0
	v_mov_b32_e32 v126, 0
	v_mov_b32_e32 v125, 0
	v_mov_b32_e32 v124, 0
	v_mov_b32_e32 v123, 0
	v_mov_b32_e32 v122, 0
	v_mov_b32_e32 v103, 0
	v_mov_b32_e32 v102, 0
	v_mov_b32_e32 v105, 0
	v_mov_b32_e32 v104, 0
	v_mov_b32_e32 v111, 0
	v_mov_b32_e32 v110, 0
	v_mov_b32_e32 v113, 0
	v_mov_b32_e32 v112, 0
	v_mov_b32_e32 v87, 0
	v_mov_b32_e32 v86, 0
	v_mov_b32_e32 v89, 0
	v_mov_b32_e32 v88, 0
	v_mov_b32_e32 v95, 0
	v_mov_b32_e32 v94, 0
	v_mov_b32_e32 v97, 0
	v_mov_b32_e32 v96, 0
	v_mov_b32_e32 v75, 0
	v_mov_b32_e32 v74, 0
	v_mov_b32_e32 v77, 0
	v_mov_b32_e32 v76, 0
	v_mov_b32_e32 v79, 0
	v_mov_b32_e32 v78, 0
	v_mov_b32_e32 v81, 0
	v_mov_b32_e32 v80, 0
	v_mov_b32_e32 v141, 0
	v_mov_b32_e32 v140, 0
	v_mov_b32_e32 v143, 0
	v_mov_b32_e32 v142, 0
	v_mov_b32_e32 v145, 0
	v_mov_b32_e32 v144, 0
	v_mov_b32_e32 v147, 0
	v_mov_b32_e32 v146, 0
	v_mov_b32_e32 v115, 0
	v_mov_b32_e32 v114, 0
	v_mov_b32_e32 v117, 0
	v_mov_b32_e32 v116, 0
	v_mov_b32_e32 v119, 0
	v_mov_b32_e32 v118, 0
	v_mov_b32_e32 v121, 0
	v_mov_b32_e32 v120, 0
	v_mov_b32_e32 v99, 0
	v_mov_b32_e32 v98, 0
	v_mov_b32_e32 v101, 0
	v_mov_b32_e32 v100, 0
	v_mov_b32_e32 v107, 0
	v_mov_b32_e32 v106, 0
	v_mov_b32_e32 v109, 0
	v_mov_b32_e32 v108, 0
	v_mov_b32_e32 v73, 0
	v_mov_b32_e32 v72, 0
	v_mov_b32_e32 v71, 0
	v_mov_b32_e32 v70, 0
	v_mov_b32_e32 v69, 0
	v_mov_b32_e32 v68, 0
	v_mov_b32_e32 v67, 0
	v_mov_b32_e32 v66, 0
	v_mov_b32_e32 v65, 0
	v_mov_b32_e32 v64, 0
	v_mov_b32_e32 v63, 0
	v_mov_b32_e32 v62, 0
	v_mov_b32_e32 v61, 0
	v_mov_b32_e32 v60, 0
	v_mov_b32_e32 v59, 0
	v_mov_b32_e32 v58, 0
	v_mov_b32_e32 v39, 0
	v_mov_b32_e32 v38, 0
	v_mov_b32_e32 v41, 0
	v_mov_b32_e32 v40, 0
	v_mov_b32_e32 v47, 0
	v_mov_b32_e32 v46, 0
	v_mov_b32_e32 v49, 0
	v_mov_b32_e32 v48, 0
	v_mov_b32_e32 v23, 0
	v_mov_b32_e32 v22, 0
	v_mov_b32_e32 v25, 0
	v_mov_b32_e32 v24, 0
	v_mov_b32_e32 v31, 0
	v_mov_b32_e32 v30, 0
	v_mov_b32_e32 v33, 0
	v_mov_b32_e32 v32, 0
	v_mov_b32_e32 v11, 0
	v_mov_b32_e32 v10, 0
	v_mov_b32_e32 v13, 0
	v_mov_b32_e32 v12, 0
	v_mov_b32_e32 v15, 0
	v_mov_b32_e32 v14, 0
	v_mov_b32_e32 v17, 0
	v_mov_b32_e32 v16, 0
	v_mov_b32_e32 v83, 0
	v_mov_b32_e32 v82, 0
	v_mov_b32_e32 v85, 0
	v_mov_b32_e32 v84, 0
	v_mov_b32_e32 v91, 0
	v_mov_b32_e32 v90, 0
	v_mov_b32_e32 v93, 0
	v_mov_b32_e32 v92, 0
	v_mov_b32_e32 v51, 0
	v_mov_b32_e32 v50, 0
	v_mov_b32_e32 v53, 0
	v_mov_b32_e32 v52, 0
	v_mov_b32_e32 v55, 0
	v_mov_b32_e32 v54, 0
	v_mov_b32_e32 v57, 0
	v_mov_b32_e32 v56, 0
	v_mov_b32_e32 v35, 0
	v_mov_b32_e32 v34, 0
	v_mov_b32_e32 v37, 0
	v_mov_b32_e32 v36, 0
	v_mov_b32_e32 v43, 0
	v_mov_b32_e32 v42, 0
	v_mov_b32_e32 v45, 0
	v_mov_b32_e32 v44, 0
	v_mov_b32_e32 v9, 0
	v_mov_b32_e32 v8, 0
	v_mov_b32_e32 v7, 0
	v_mov_b32_e32 v6, 0
	v_mov_b32_e32 v5, 0
	v_mov_b32_e32 v4, 0
	v_mov_b32_e32 v3, 0
	v_mov_b32_e32 v2, 0
	s_cbranch_vccnz .LBB0_432
	s_and_b64 s[8:9], s[4:5], exec
	s_cselect_b32 s25, s29, s35
	s_cselect_b32 s27, s28, s34
	s_cselect_b32 s79, s31, s37
	s_cselect_b32 s91, s30, s36
	s_add_u32 s34, s34, 0x80080
	s_addc_u32 s35, s35, 0
	s_add_u32 vcc_lo, s36, 0x100
	s_addc_u32 vcc_hi, s37, 0
	s_mov_b32 s36, 0
	v_mov_b64_e32 v[2:3], 0
	v_mov_b64_e32 v[4:5], 0
	v_mov_b64_e32 v[6:7], 0
	v_mov_b64_e32 v[8:9], 0
	v_mov_b64_e32 v[10:11], 0
	v_mov_b64_e32 v[12:13], 0
	v_mov_b64_e32 v[14:15], 0
	v_mov_b64_e32 v[16:17], 0
	v_mov_b64_e32 v[18:19], 0
	v_mov_b64_e32 v[20:21], 0
	v_mov_b64_e32 v[22:23], 0
	v_mov_b64_e32 v[24:25], 0
	v_mov_b64_e32 v[26:27], 0
	v_mov_b64_e32 v[28:29], 0
	v_mov_b64_e32 v[30:31], 0
	v_mov_b64_e32 v[32:33], 0
	v_mov_b64_e32 v[34:35], 0
	v_mov_b64_e32 v[36:37], 0
	v_mov_b64_e32 v[38:39], 0
	v_mov_b64_e32 v[40:41], 0
	v_mov_b64_e32 v[42:43], 0
	v_mov_b64_e32 v[44:45], 0
	v_mov_b64_e32 v[46:47], 0
	v_mov_b64_e32 v[48:49], 0
	v_mov_b64_e32 v[50:51], 0
	v_mov_b64_e32 v[52:53], 0
	v_mov_b64_e32 v[54:55], 0
	v_mov_b64_e32 v[56:57], 0
	v_mov_b64_e32 v[58:59], 0
	v_mov_b64_e32 v[60:61], 0
	v_mov_b64_e32 v[62:63], 0
	v_mov_b64_e32 v[64:65], 0
	v_mov_b64_e32 v[66:67], 0
	v_mov_b64_e32 v[68:69], 0
	v_mov_b64_e32 v[70:71], 0
	v_mov_b64_e32 v[72:73], 0
	v_mov_b64_e32 v[74:75], 0
	v_mov_b64_e32 v[76:77], 0
	v_mov_b64_e32 v[78:79], 0
	v_mov_b64_e32 v[80:81], 0
	v_mov_b64_e32 v[82:83], 0
	v_mov_b64_e32 v[84:85], 0
	v_mov_b64_e32 v[86:87], 0
	v_mov_b64_e32 v[88:89], 0
	v_mov_b64_e32 v[90:91], 0
	v_mov_b64_e32 v[92:93], 0
	v_mov_b64_e32 v[94:95], 0
	v_mov_b64_e32 v[96:97], 0
	v_mov_b64_e32 v[98:99], 0
	v_mov_b64_e32 v[100:101], 0
	v_mov_b64_e32 v[102:103], 0
	v_mov_b64_e32 v[104:105], 0
	v_mov_b64_e32 v[106:107], 0
	v_mov_b64_e32 v[108:109], 0
	v_mov_b64_e32 v[110:111], 0
	v_mov_b64_e32 v[112:113], 0
	v_mov_b64_e32 v[114:115], 0
	v_mov_b64_e32 v[116:117], 0
	v_mov_b64_e32 v[118:119], 0
	v_mov_b64_e32 v[120:121], 0
	v_mov_b64_e32 v[122:123], 0
	v_mov_b64_e32 v[124:125], 0
	v_mov_b64_e32 v[126:127], 0
	v_mov_b64_e32 v[128:129], 0

.LBB0_458:
	s_andn2_b64 vcc, exec, s[18:19]
	v_mov_b64_e32 v[2:3], 0
	v_mov_b64_e32 v[4:5], 0
	v_mov_b64_e32 v[6:7], 0
	v_mov_b64_e32 v[8:9], 0
	v_mov_b64_e32 v[10:11], 0
	v_mov_b64_e32 v[12:13], 0
	v_mov_b64_e32 v[14:15], 0
	v_mov_b64_e32 v[16:17], 0
	v_mov_b64_e32 v[18:19], 0
	v_mov_b64_e32 v[20:21], 0
	v_mov_b64_e32 v[22:23], 0
	v_mov_b64_e32 v[24:25], 0
	v_mov_b64_e32 v[26:27], 0
	v_mov_b64_e32 v[28:29], 0
	v_mov_b64_e32 v[30:31], 0
	v_mov_b64_e32 v[32:33], 0
	v_mov_b64_e32 v[34:35], 0
	v_mov_b64_e32 v[36:37], 0
	v_mov_b64_e32 v[38:39], 0
	v_mov_b64_e32 v[40:41], 0
	v_mov_b64_e32 v[42:43], 0
	v_mov_b64_e32 v[44:45], 0
	v_mov_b64_e32 v[46:47], 0
	v_mov_b64_e32 v[48:49], 0
	v_mov_b64_e32 v[50:51], 0
	v_mov_b64_e32 v[52:53], 0
	v_mov_b64_e32 v[54:55], 0
	v_mov_b64_e32 v[56:57], 0
	v_mov_b64_e32 v[58:59], 0
	v_mov_b64_e32 v[60:61], 0
	v_mov_b64_e32 v[62:63], 0
	v_mov_b64_e32 v[64:65], 0
	v_mov_b64_e32 v[66:67], 0
	v_mov_b64_e32 v[68:69], 0
	v_mov_b64_e32 v[70:71], 0
	v_mov_b64_e32 v[72:73], 0
	v_mov_b64_e32 v[74:75], 0
	v_mov_b64_e32 v[76:77], 0
	v_mov_b64_e32 v[78:79], 0
	v_mov_b64_e32 v[80:81], 0
	v_mov_b64_e32 v[82:83], 0
	v_mov_b64_e32 v[84:85], 0
	v_mov_b64_e32 v[86:87], 0
	v_mov_b64_e32 v[88:89], 0
	v_mov_b64_e32 v[90:91], 0
	v_mov_b64_e32 v[92:93], 0
	v_mov_b64_e32 v[94:95], 0
	v_mov_b64_e32 v[96:97], 0
	v_mov_b64_e32 v[98:99], 0
	v_mov_b64_e32 v[100:101], 0
	v_mov_b64_e32 v[102:103], 0
	v_mov_b64_e32 v[104:105], 0
	v_mov_b64_e32 v[106:107], 0
	v_mov_b64_e32 v[108:109], 0
	v_mov_b64_e32 v[110:111], 0
	v_mov_b64_e32 v[112:113], 0
	v_mov_b64_e32 v[114:115], 0
	v_mov_b64_e32 v[116:117], 0
	v_mov_b64_e32 v[118:119], 0
	v_mov_b64_e32 v[120:121], 0
	v_mov_b64_e32 v[122:123], 0
	v_mov_b64_e32 v[124:125], 0
	v_mov_b64_e32 v[126:127], 0
	v_mov_b64_e32 v[128:129], 0
	s_cbranch_vccnz .LBB0_461
	s_add_u32 s75, s26, 0x100
	v_mov_b32_e32 v2, 0
	s_addc_u32 s77, s27, 0
	s_mov_b32 s28, 0

.LBB0_501:
	s_ashr_i32 s23, s22, 31
	s_lshl_b64 s[8:9], s[22:23], 19
	s_add_u32 s26, s60, s8
	s_addc_u32 s27, s61, s9
	s_ashr_i32 s21, s20, 31
	s_lshl_b64 s[8:9], s[20:21], 19
	v_readlane_b32 s28, v255, 43
	v_readlane_b32 s29, v255, 44
	s_add_u32 s28, s28, s8
	s_addc_u32 s29, s29, s9
	s_andn2_b64 vcc, exec, s[16:17]
	v_mov_b64_e32 v[2:3], 0
	v_mov_b64_e32 v[4:5], 0
	v_mov_b64_e32 v[6:7], 0
	v_mov_b64_e32 v[8:9], 0
	v_mov_b64_e32 v[10:11], 0
	v_mov_b64_e32 v[12:13], 0
	v_mov_b64_e32 v[14:15], 0
	v_mov_b64_e32 v[16:17], 0
	v_mov_b64_e32 v[18:19], 0
	v_mov_b64_e32 v[20:21], 0
	v_mov_b64_e32 v[22:23], 0
	v_mov_b64_e32 v[24:25], 0
	v_mov_b64_e32 v[26:27], 0
	v_mov_b64_e32 v[28:29], 0
	v_mov_b64_e32 v[30:31], 0
	v_mov_b64_e32 v[32:33], 0
	v_mov_b64_e32 v[34:35], 0
	v_mov_b64_e32 v[36:37], 0
	v_mov_b64_e32 v[38:39], 0
	v_mov_b64_e32 v[40:41], 0
	v_mov_b64_e32 v[42:43], 0
	v_mov_b64_e32 v[44:45], 0
	v_mov_b64_e32 v[46:47], 0
	v_mov_b64_e32 v[48:49], 0
	v_mov_b64_e32 v[50:51], 0
	v_mov_b64_e32 v[52:53], 0
	v_mov_b64_e32 v[54:55], 0
	v_mov_b64_e32 v[56:57], 0
	v_mov_b64_e32 v[58:59], 0
	v_mov_b64_e32 v[60:61], 0
	v_mov_b64_e32 v[62:63], 0
	v_mov_b64_e32 v[64:65], 0
	v_mov_b64_e32 v[66:67], 0
	v_mov_b64_e32 v[68:69], 0
	v_mov_b64_e32 v[70:71], 0
	v_mov_b64_e32 v[72:73], 0
	v_mov_b64_e32 v[74:75], 0
	v_mov_b64_e32 v[76:77], 0
	v_mov_b64_e32 v[78:79], 0
	v_mov_b64_e32 v[80:81], 0
	v_mov_b64_e32 v[82:83], 0
	v_mov_b64_e32 v[84:85], 0
	v_mov_b64_e32 v[86:87], 0
	v_mov_b64_e32 v[88:89], 0
	v_mov_b64_e32 v[90:91], 0
	v_mov_b64_e32 v[92:93], 0
	v_mov_b64_e32 v[94:95], 0
	v_mov_b64_e32 v[96:97], 0
	v_mov_b64_e32 v[98:99], 0
	v_mov_b64_e32 v[100:101], 0
	v_mov_b64_e32 v[102:103], 0
	v_mov_b64_e32 v[104:105], 0
	v_mov_b64_e32 v[106:107], 0
	v_mov_b64_e32 v[108:109], 0
	v_mov_b64_e32 v[110:111], 0
	v_mov_b64_e32 v[112:113], 0
	v_mov_b64_e32 v[114:115], 0
	v_mov_b64_e32 v[116:117], 0
	v_mov_b64_e32 v[118:119], 0
	v_mov_b64_e32 v[120:121], 0
	v_mov_b64_e32 v[122:123], 0
	v_mov_b64_e32 v[124:125], 0
	v_mov_b64_e32 v[126:127], 0
	v_mov_b64_e32 v[128:129], 0
	s_cbranch_vccnz .LBB0_505
	s_and_b64 s[8:9], s[4:5], exec
	s_cselect_b32 s21, s27, s31
	s_cselect_b32 s23, s26, s30
	s_cselect_b32 s70, s29, s35
	s_cselect_b32 s71, s28, s34
	s_add_u32 s30, s30, 0x40080
	s_addc_u32 s31, s31, 0
	s_add_u32 s74, s34, 0x100
	s_addc_u32 s75, s35, 0
	s_mov_b32 s34, 0
	v_mov_b64_e32 v[2:3], 0
	v_mov_b64_e32 v[4:5], 0
	v_mov_b64_e32 v[6:7], 0
	v_mov_b64_e32 v[8:9], 0
	v_mov_b64_e32 v[10:11], 0
	v_mov_b64_e32 v[12:13], 0
	v_mov_b64_e32 v[14:15], 0
	v_mov_b64_e32 v[16:17], 0
	v_mov_b64_e32 v[18:19], 0
	v_mov_b64_e32 v[20:21], 0
	v_mov_b64_e32 v[22:23], 0
	v_mov_b64_e32 v[24:25], 0
	v_mov_b64_e32 v[26:27], 0
	v_mov_b64_e32 v[28:29], 0
	v_mov_b64_e32 v[30:31], 0
	v_mov_b64_e32 v[32:33], 0
	v_mov_b64_e32 v[34:35], 0
	v_mov_b64_e32 v[36:37], 0
	v_mov_b64_e32 v[38:39], 0
	v_mov_b64_e32 v[40:41], 0
	v_mov_b64_e32 v[42:43], 0
	v_mov_b64_e32 v[44:45], 0
	v_mov_b64_e32 v[46:47], 0
	v_mov_b64_e32 v[48:49], 0
	v_mov_b64_e32 v[50:51], 0
	v_mov_b64_e32 v[52:53], 0
	v_mov_b64_e32 v[54:55], 0
	v_mov_b64_e32 v[56:57], 0
	v_mov_b64_e32 v[58:59], 0
	v_mov_b64_e32 v[60:61], 0
	v_mov_b64_e32 v[62:63], 0
	v_mov_b64_e32 v[64:65], 0
	v_mov_b64_e32 v[66:67], 0
	v_mov_b64_e32 v[68:69], 0
	v_mov_b64_e32 v[70:71], 0
	v_mov_b64_e32 v[72:73], 0
	v_mov_b64_e32 v[74:75], 0
	v_mov_b64_e32 v[76:77], 0
	v_mov_b64_e32 v[78:79], 0
	v_mov_b64_e32 v[80:81], 0
	v_mov_b64_e32 v[82:83], 0
	v_mov_b64_e32 v[84:85], 0
	v_mov_b64_e32 v[86:87], 0
	v_mov_b64_e32 v[88:89], 0
	v_mov_b64_e32 v[90:91], 0
	v_mov_b64_e32 v[92:93], 0
	v_mov_b64_e32 v[94:95], 0
	v_mov_b64_e32 v[96:97], 0
	v_mov_b64_e32 v[98:99], 0
	v_mov_b64_e32 v[100:101], 0
	v_mov_b64_e32 v[102:103], 0
	v_mov_b64_e32 v[104:105], 0
	v_mov_b64_e32 v[106:107], 0
	v_mov_b64_e32 v[108:109], 0
	v_mov_b64_e32 v[110:111], 0
	v_mov_b64_e32 v[112:113], 0
	v_mov_b64_e32 v[114:115], 0
	v_mov_b64_e32 v[116:117], 0
	v_mov_b64_e32 v[118:119], 0
	v_mov_b64_e32 v[120:121], 0
	v_mov_b64_e32 v[122:123], 0
	v_mov_b64_e32 v[124:125], 0
	v_mov_b64_e32 v[126:127], 0
	v_mov_b64_e32 v[128:129], 0

.LBB0_539:
	s_andn2_b64 vcc, exec, s[16:17]
	v_mov_b64_e32 v[2:3], 0
	v_mov_b64_e32 v[4:5], 0
	v_mov_b64_e32 v[6:7], 0
	v_mov_b64_e32 v[8:9], 0
	v_mov_b64_e32 v[10:11], 0
	v_mov_b64_e32 v[12:13], 0
	v_mov_b64_e32 v[14:15], 0
	v_mov_b64_e32 v[16:17], 0
	v_mov_b64_e32 v[18:19], 0
	v_mov_b64_e32 v[20:21], 0
	v_mov_b64_e32 v[22:23], 0
	v_mov_b64_e32 v[24:25], 0
	v_mov_b64_e32 v[26:27], 0
	v_mov_b64_e32 v[28:29], 0
	v_mov_b64_e32 v[30:31], 0
	v_mov_b64_e32 v[32:33], 0
	v_mov_b64_e32 v[34:35], 0
	v_mov_b64_e32 v[36:37], 0
	v_mov_b64_e32 v[38:39], 0
	v_mov_b64_e32 v[40:41], 0
	v_mov_b64_e32 v[42:43], 0
	v_mov_b64_e32 v[44:45], 0
	v_mov_b64_e32 v[46:47], 0
	v_mov_b64_e32 v[48:49], 0
	v_mov_b64_e32 v[50:51], 0
	v_mov_b64_e32 v[52:53], 0
	v_mov_b64_e32 v[54:55], 0
	v_mov_b64_e32 v[56:57], 0
	v_mov_b64_e32 v[58:59], 0
	v_mov_b64_e32 v[60:61], 0
	v_mov_b64_e32 v[62:63], 0
	v_mov_b64_e32 v[64:65], 0
	v_mov_b64_e32 v[66:67], 0
	v_mov_b64_e32 v[68:69], 0
	v_mov_b64_e32 v[70:71], 0
	v_mov_b64_e32 v[72:73], 0
	v_mov_b64_e32 v[74:75], 0
	v_mov_b64_e32 v[76:77], 0
	v_mov_b64_e32 v[78:79], 0
	v_mov_b64_e32 v[80:81], 0
	v_mov_b64_e32 v[82:83], 0
	v_mov_b64_e32 v[84:85], 0
	v_mov_b64_e32 v[86:87], 0
	v_mov_b64_e32 v[88:89], 0
	v_mov_b64_e32 v[90:91], 0
	v_mov_b64_e32 v[92:93], 0
	v_mov_b64_e32 v[94:95], 0
	v_mov_b64_e32 v[96:97], 0
	v_mov_b64_e32 v[98:99], 0
	v_mov_b64_e32 v[100:101], 0
	v_mov_b64_e32 v[102:103], 0
	v_mov_b64_e32 v[104:105], 0
	v_mov_b64_e32 v[106:107], 0
	v_mov_b64_e32 v[108:109], 0
	v_mov_b64_e32 v[110:111], 0
	v_mov_b64_e32 v[112:113], 0
	v_mov_b64_e32 v[114:115], 0
	v_mov_b64_e32 v[116:117], 0
	v_mov_b64_e32 v[118:119], 0
	v_mov_b64_e32 v[120:121], 0
	v_mov_b64_e32 v[122:123], 0
	v_mov_b64_e32 v[124:125], 0
	v_mov_b64_e32 v[126:127], 0
	v_mov_b64_e32 v[128:129], 0
	s_cbranch_vccnz .LBB0_543
	s_add_u32 s62, s24, 0x100
	v_mov_b32_e32 v2, 0
	s_addc_u32 s67, s25, 0
	s_mov_b32 s26, 0

.LBB0_575:
	s_ashr_i32 s21, s20, 31
	s_lshl_b64 s[22:23], s[20:21], 19
	s_add_u32 s22, s60, s22
	s_addc_u32 s23, s61, s23
	s_ashr_i32 s19, s18, 31
	s_lshl_b64 s[24:25], s[18:19], 19
	s_add_u32 s24, s34, s24
	s_addc_u32 s25, s35, s25
	s_andn2_b64 vcc, exec, s[12:13]
	v_mov_b64_e32 v[2:3], 0
	v_mov_b64_e32 v[4:5], 0
	v_mov_b64_e32 v[6:7], 0
	v_mov_b64_e32 v[8:9], 0
	v_mov_b64_e32 v[10:11], 0
	v_mov_b64_e32 v[12:13], 0
	v_mov_b64_e32 v[14:15], 0
	v_mov_b64_e32 v[16:17], 0
	v_mov_b64_e32 v[18:19], 0
	v_mov_b64_e32 v[20:21], 0
	v_mov_b64_e32 v[22:23], 0
	v_mov_b64_e32 v[24:25], 0
	v_mov_b64_e32 v[26:27], 0
	v_mov_b64_e32 v[28:29], 0
	v_mov_b64_e32 v[30:31], 0
	v_mov_b64_e32 v[32:33], 0
	v_mov_b64_e32 v[34:35], 0
	v_mov_b64_e32 v[36:37], 0
	v_mov_b64_e32 v[38:39], 0
	v_mov_b64_e32 v[40:41], 0
	v_mov_b64_e32 v[42:43], 0
	v_mov_b64_e32 v[44:45], 0
	v_mov_b64_e32 v[46:47], 0
	v_mov_b64_e32 v[48:49], 0
	v_mov_b64_e32 v[50:51], 0
	v_mov_b64_e32 v[52:53], 0
	v_mov_b64_e32 v[54:55], 0
	v_mov_b64_e32 v[56:57], 0
	v_mov_b64_e32 v[58:59], 0
	v_mov_b64_e32 v[60:61], 0
	v_mov_b64_e32 v[62:63], 0
	v_mov_b64_e32 v[64:65], 0
	v_mov_b64_e32 v[66:67], 0
	v_mov_b64_e32 v[68:69], 0
	v_mov_b64_e32 v[70:71], 0
	v_mov_b64_e32 v[72:73], 0
	v_mov_b64_e32 v[74:75], 0
	v_mov_b64_e32 v[76:77], 0
	v_mov_b64_e32 v[78:79], 0
	v_mov_b64_e32 v[80:81], 0
	v_mov_b64_e32 v[82:83], 0
	v_mov_b64_e32 v[84:85], 0
	v_mov_b64_e32 v[86:87], 0
	v_mov_b64_e32 v[88:89], 0
	v_mov_b64_e32 v[90:91], 0
	v_mov_b64_e32 v[92:93], 0
	v_mov_b64_e32 v[94:95], 0
	v_mov_b64_e32 v[96:97], 0
	v_mov_b64_e32 v[98:99], 0
	v_mov_b64_e32 v[100:101], 0
	v_mov_b64_e32 v[102:103], 0
	v_mov_b64_e32 v[104:105], 0
	v_mov_b64_e32 v[106:107], 0
	v_mov_b64_e32 v[108:109], 0
	v_mov_b64_e32 v[110:111], 0
	v_mov_b64_e32 v[112:113], 0
	v_mov_b64_e32 v[114:115], 0
	v_mov_b64_e32 v[116:117], 0
	v_mov_b64_e32 v[118:119], 0
	v_mov_b64_e32 v[120:121], 0
	v_mov_b64_e32 v[122:123], 0
	v_mov_b64_e32 v[124:125], 0
	v_mov_b64_e32 v[126:127], 0
	v_mov_b64_e32 v[128:129], 0
	s_cbranch_vccnz .LBB0_579
	s_and_b64 s[30:31], s[4:5], exec
	s_cselect_b32 s7, s23, s27
	s_cselect_b32 s9, s22, s26
	s_cselect_b32 s19, s25, s29
	s_cselect_b32 s21, s24, s28
	s_add_u32 s26, s26, 0x40080
	s_addc_u32 s27, s27, 0
	s_add_u32 s71, s28, 0x100
	s_addc_u32 s74, s29, 0
	s_mov_b32 s28, 0
	v_mov_b64_e32 v[2:3], 0
	v_mov_b64_e32 v[4:5], 0
	v_mov_b64_e32 v[6:7], 0
	v_mov_b64_e32 v[8:9], 0
	v_mov_b64_e32 v[10:11], 0
	v_mov_b64_e32 v[12:13], 0
	v_mov_b64_e32 v[14:15], 0
	v_mov_b64_e32 v[16:17], 0
	v_mov_b64_e32 v[18:19], 0
	v_mov_b64_e32 v[20:21], 0
	v_mov_b64_e32 v[22:23], 0
	v_mov_b64_e32 v[24:25], 0
	v_mov_b64_e32 v[26:27], 0
	v_mov_b64_e32 v[28:29], 0
	v_mov_b64_e32 v[30:31], 0
	v_mov_b64_e32 v[32:33], 0
	v_mov_b64_e32 v[34:35], 0
	v_mov_b64_e32 v[36:37], 0
	v_mov_b64_e32 v[38:39], 0
	v_mov_b64_e32 v[40:41], 0
	v_mov_b64_e32 v[42:43], 0
	v_mov_b64_e32 v[44:45], 0
	v_mov_b64_e32 v[46:47], 0
	v_mov_b64_e32 v[48:49], 0
	v_mov_b64_e32 v[50:51], 0
	v_mov_b64_e32 v[52:53], 0
	v_mov_b64_e32 v[54:55], 0
	v_mov_b64_e32 v[56:57], 0
	v_mov_b64_e32 v[58:59], 0
	v_mov_b64_e32 v[60:61], 0
	v_mov_b64_e32 v[62:63], 0
	v_mov_b64_e32 v[64:65], 0
	v_mov_b64_e32 v[66:67], 0
	v_mov_b64_e32 v[68:69], 0
	v_mov_b64_e32 v[70:71], 0
	v_mov_b64_e32 v[72:73], 0
	v_mov_b64_e32 v[74:75], 0
	v_mov_b64_e32 v[76:77], 0
	v_mov_b64_e32 v[78:79], 0
	v_mov_b64_e32 v[80:81], 0
	v_mov_b64_e32 v[82:83], 0
	v_mov_b64_e32 v[84:85], 0
	v_mov_b64_e32 v[86:87], 0
	v_mov_b64_e32 v[88:89], 0
	v_mov_b64_e32 v[90:91], 0
	v_mov_b64_e32 v[92:93], 0
	v_mov_b64_e32 v[94:95], 0
	v_mov_b64_e32 v[96:97], 0
	v_mov_b64_e32 v[98:99], 0
	v_mov_b64_e32 v[100:101], 0
	v_mov_b64_e32 v[102:103], 0
	v_mov_b64_e32 v[104:105], 0
	v_mov_b64_e32 v[106:107], 0
	v_mov_b64_e32 v[108:109], 0
	v_mov_b64_e32 v[110:111], 0
	v_mov_b64_e32 v[112:113], 0
	v_mov_b64_e32 v[114:115], 0
	v_mov_b64_e32 v[116:117], 0
	v_mov_b64_e32 v[118:119], 0
	v_mov_b64_e32 v[120:121], 0
	v_mov_b64_e32 v[122:123], 0
	v_mov_b64_e32 v[124:125], 0
	v_mov_b64_e32 v[126:127], 0
	v_mov_b64_e32 v[128:129], 0

.LBB0_914:
	s_andn2_b64 vcc, exec, s[12:13]
	v_mov_b64_e32 v[2:3], 0
	v_mov_b64_e32 v[4:5], 0
	v_mov_b64_e32 v[6:7], 0
	v_mov_b64_e32 v[8:9], 0
	v_mov_b64_e32 v[10:11], 0
	v_mov_b64_e32 v[12:13], 0
	v_mov_b64_e32 v[14:15], 0
	v_mov_b64_e32 v[16:17], 0
	v_mov_b64_e32 v[18:19], 0
	v_mov_b64_e32 v[20:21], 0
	v_mov_b64_e32 v[22:23], 0
	v_mov_b64_e32 v[24:25], 0
	v_mov_b64_e32 v[26:27], 0
	v_mov_b64_e32 v[28:29], 0
	v_mov_b64_e32 v[30:31], 0
	v_mov_b64_e32 v[32:33], 0
	v_mov_b64_e32 v[34:35], 0
	v_mov_b64_e32 v[36:37], 0
	v_mov_b64_e32 v[38:39], 0
	v_mov_b64_e32 v[40:41], 0
	v_mov_b64_e32 v[42:43], 0
	v_mov_b64_e32 v[44:45], 0
	v_mov_b64_e32 v[46:47], 0
	v_mov_b64_e32 v[48:49], 0
	v_mov_b64_e32 v[50:51], 0
	v_mov_b64_e32 v[52:53], 0
	v_mov_b64_e32 v[54:55], 0
	v_mov_b64_e32 v[56:57], 0
	v_mov_b64_e32 v[58:59], 0
	v_mov_b64_e32 v[60:61], 0
	v_mov_b64_e32 v[62:63], 0
	v_mov_b64_e32 v[64:65], 0
	v_mov_b64_e32 v[66:67], 0
	v_mov_b64_e32 v[68:69], 0
	v_mov_b64_e32 v[70:71], 0
	v_mov_b64_e32 v[72:73], 0
	v_mov_b64_e32 v[74:75], 0
	v_mov_b64_e32 v[76:77], 0
	v_mov_b64_e32 v[78:79], 0
	v_mov_b64_e32 v[80:81], 0
	v_mov_b64_e32 v[82:83], 0
	v_mov_b64_e32 v[84:85], 0
	v_mov_b64_e32 v[86:87], 0
	v_mov_b64_e32 v[88:89], 0
	v_mov_b64_e32 v[90:91], 0
	v_mov_b64_e32 v[92:93], 0
	v_mov_b64_e32 v[94:95], 0
	v_mov_b64_e32 v[96:97], 0
	v_mov_b64_e32 v[98:99], 0
	v_mov_b64_e32 v[100:101], 0
	v_mov_b64_e32 v[102:103], 0
	v_mov_b64_e32 v[104:105], 0
	v_mov_b64_e32 v[106:107], 0
	v_mov_b64_e32 v[108:109], 0
	v_mov_b64_e32 v[110:111], 0
	v_mov_b64_e32 v[112:113], 0
	v_mov_b64_e32 v[114:115], 0
	v_mov_b64_e32 v[116:117], 0
	v_mov_b64_e32 v[118:119], 0
	v_mov_b64_e32 v[120:121], 0
	v_mov_b64_e32 v[122:123], 0
	v_mov_b64_e32 v[124:125], 0
	v_mov_b64_e32 v[126:127], 0
	v_mov_b64_e32 v[128:129], 0
	s_cbranch_vccnz .LBB0_917
	s_add_u32 s18, s18, 0x80
	s_addc_u32 s19, s19, 0
	s_add_u32 s56, s20, 0x100
	v_mov_b32_e32 v2, 0
	s_addc_u32 s57, s21, 0
	s_mov_b32 s20, 0
